# GEMM tile prologues (gemm_in, out, ple): no vmcnt(0) store drain before the first LDS-DMA group
# speedup vs baseline: 1.0114x; 1.0026x over previous
; DI void gemm_dma(f32x4 (&acc)[4][4], const bf16_t* Ap, int lda, const bf16_t* Bp, int ldb, int K, char* lds) {
;   const int tid = tid_(), wave = __builtin_amdgcn_readfirstlane(tid >> 6), lane = tid & 63;
;   const int wm = wave >> 1, wn = wave & 1, l15 = lane & 15, quad = lane >> 4;
;   const int nk = K / 64;
;   const int lrow = lane >> 3, lpc = lane & 7;
;   const bf16_t* ga[4]; const bf16_t* gb[4];
; #pragma unroll
;   for (int i = 0; i < 4; ++i) {
;     const int row = (wave * 4 + i) * 8 + lrow; const int q = lpc ^ (row & 7);
;     ga[i] = Ap + (size_t)row * lda + q * 8; gb[i] = Bp + (size_t)row * ldb + q * 8;
;   }
;   auto issue = [&](int kt) {
;     char* sb = lds + (kt & 1) * 32768 + wave * 4096;
; #pragma unroll
;     for (int i = 0; i < 4; ++i) {
;       __builtin_amdgcn_global_load_lds((const unsigned*)(ga[i] + kt * 64), (LASP unsigned*)(sb + i * 1024), 16, 0, 0);
;       __builtin_amdgcn_global_load_lds((const unsigned*)(gb[i] + kt * 64), (LASP unsigned*)(sb + 16384 + i * 1024), 16, 0, 0);
;     }
;   };
;   const int sw = l15 & 7;
;   const unsigned lbase = (unsigned)(size_t)(LASP char*)lds;
;   const unsigned a0 = (unsigned)((wm * 64 + l15) * 128 + ((quad ^ sw) * 16)), a1 = (unsigned)((wm * 64 + l15) * 128 + (((4 + quad) ^ sw) * 16));
;   const unsigned b0 = 16384u + (unsigned)((wn * 64 + l15) * 128 + ((quad ^ sw) * 16)), b1 = 16384u + (unsigned)((wn * 64 + l15) * 128 + (((4 + quad) ^ sw) * 16));
;   asm volatile("s_waitcnt vmcnt(0)" ::: "memory");
;   __builtin_amdgcn_s_barrier();
; DI int xcd_tile(int r, int T) {
;   const int x = blockIdx.x & 7, j = blockIdx.x >> 3, nb = gridDim.x >> 3;
;   if (j >= nb) return -1;
;   const int start = (int)(((long)x * T) / 8), end = (int)(((long)(x + 1) * T) / 8);
;   const int g = start + r * nb + j;
;   return g < end ? g : -1;
; }
; DI void phase_gemm_in(const Params& p, int l, char* lds) {
;   const int tid = tid_(), wave = __builtin_amdgcn_readfirstlane(tid >> 6), lane = tid & 63;
;   const int wm = wave >> 1, wn = wave & 1, l15 = lane & 15, quad = lane >> 4;
;   const bf16_t* Wt = p.wt_in;
;   const int NTN = 49, NTM = 132;
;   for (int r = 0;; ++r) {
;     const int g = xcd_tile(r, NTN * NTM); if (g < 0) break;
;     int mt, nt; tile_decode(g, NTM, NTN, mt, nt);
;     f32x4 acc[4][4]; zero_acc(acc);
;     gemm_dma(acc, p.hn + (size_t)mt * 128 * DM, DM, Wt + (size_t)nt * 128 * DM, DM, DM, lds);
.LBB0_68:
	s_mul_hi_u32 s0, s20, 0x5397829d
	s_lshr_b32 s21, s0, 7
	s_lshl_b32 s0, s21, 3
	s_sub_i32 s1, 0x84, s0
	s_min_i32 s1, s1, 8
	s_abs_i32 s2, s1
	v_cvt_f32_u32_e32 v0, s2
	s_sub_i32 s24, 0, s2
	s_mul_i32 s3, s21, 0xfffffe78
	s_add_i32 s3, s3, s20
	v_rcp_iflag_f32_e32 v0, v0
	s_abs_i32 s22, s3
	s_xor_b32 s23, s3, s1
	s_ashr_i32 s23, s23, 31
	v_mul_f32_e32 v0, 0x4f7ffffe, v0
	v_cvt_u32_f32_e32 v0, v0
	v_readlane_b32 s68, v251, 49
	v_readlane_b32 s72, v251, 53
	v_mov_b32_e32 v26, v212
	v_readfirstlane_b32 s25, v0
	s_mul_i32 s24, s24, s25
	s_mul_hi_u32 s24, s25, s24
	s_add_i32 s25, s25, s24
	s_mul_hi_u32 s24, s22, s25
	s_mul_i32 s25, s24, s2
	s_sub_i32 s22, s22, s25
	s_add_i32 s26, s24, 1
	s_sub_i32 s25, s22, s2
	s_cmp_ge_u32 s22, s2
	s_cselect_b32 s24, s26, s24
	s_cselect_b32 s22, s25, s22
	s_add_i32 s25, s24, 1
	s_cmp_ge_u32 s22, s2
	s_cselect_b32 s2, s25, s24
	s_add_i32 s3, s3, s0
	s_xor_b32 s0, s2, s23
	s_sub_i32 s0, s0, s23
	s_mul_i32 s30, s0, s1
	s_sub_i32 s2, s3, s30
	s_ashr_i32 s3, s2, 31
	s_lshl_b64 s[22:23], s[2:3], 18
	s_add_u32 s24, s8, s22
	s_addc_u32 s25, s9, s23
	s_ashr_i32 s1, s0, 31
	s_lshl_b64 s[22:23], s[0:1], 18
	v_readlane_b32 s73, v251, 54
	s_add_u32 s26, s72, s22
	s_addc_u32 s27, s73, s23
	v_readfirstlane_b32 s1, v26
	s_ashr_i32 s3, s1, 6
	v_bfe_u32 v0, v26, 3, 3
	s_waitcnt lgkmcnt(0)
	v_lshl_or_b32 v2, s3, 5, v0
	v_bitop3_b32 v0, v0, v26, 7 bitop3:0x78
	v_bfe_u32 v27, v26, 4, 2
	v_and_b32_e32 v28, 7, v26
	v_lshlrev_b32_e32 v0, 4, v0
	v_ashrrev_i32_e32 v3, 31, v2
	v_and_b32_e32 v29, 15, v26
	v_lshl_add_u64 v[4:5], s[24:25], 0, v[0:1]
	v_lshlrev_b64 v[8:9], 11, v[2:3]
	v_or_b32_e32 v14, 8, v2
	s_lshr_b32 s24, s1, 1
	v_bitop3_b32 v26, v27, v26, 7 bitop3:0x78
	v_bitop3_b32 v27, v27, v28, 4 bitop3:0x36
	v_and_or_b32 v28, s1, 64, v29
	s_lshl_b32 s1, s3, 12
	v_lshl_add_u64 v[6:7], s[26:27], 0, v[0:1]
	v_lshl_add_u64 v[10:11], v[4:5], 0, v[8:9]
	v_ashrrev_i32_e32 v15, 31, v14
	s_nop 0
	s_barrier
	s_add_i32 s3, s1, 0x4000
	s_mov_b32 m0, s1
	v_lshl_add_u64 v[12:13], v[6:7], 0, v[8:9]
	v_lshlrev_b64 v[14:15], 11, v[14:15]
	v_or_b32_e32 v20, 16, v2
	global_load_lds_dwordx4 v[10:11], off
	s_mov_b32 m0, s3
	v_lshl_add_u64 v[16:17], v[4:5], 0, v[14:15]
	v_ashrrev_i32_e32 v21, 31, v20
	global_load_lds_dwordx4 v[12:13], off
	s_or_b32 m0, s1, 0x400
	v_lshl_add_u64 v[18:19], v[6:7], 0, v[14:15]
	v_lshlrev_b64 v[20:21], 11, v[20:21]
	v_or_b32_e32 v2, 24, v2
	global_load_lds_dwordx4 v[16:17], off
	s_add_i32 m0, s1, 0x4400
	v_lshl_add_u64 v[22:23], v[4:5], 0, v[20:21]
	v_ashrrev_i32_e32 v3, 31, v2
	global_load_lds_dwordx4 v[18:19], off
	s_or_b32 m0, s1, 0x800
	v_lshl_add_u64 v[24:25], v[6:7], 0, v[20:21]
	v_lshlrev_b64 v[2:3], 11, v[2:3]
	global_load_lds_dwordx4 v[22:23], off
	s_add_i32 m0, s1, 0x4800
	v_lshl_add_u64 v[4:5], v[4:5], 0, v[2:3]
	global_load_lds_dwordx4 v[24:25], off
	s_or_b32 m0, s1, 0xc00
	v_lshl_add_u64 v[6:7], v[6:7], 0, v[2:3]
	global_load_lds_dwordx4 v[4:5], off
	s_add_i32 m0, s1, 0x4c00
	s_sub_i32 s3, s20, s30
	global_load_lds_dwordx4 v[6:7], off
	s_mulk_i32 s21, 0x180
	s_sub_i32 s20, s3, s21
	s_ashr_i32 s21, s20, 31
	s_and_b32 s24, s24, 0x1ffffc0
	s_lshl_b64 s[20:21], s[20:21], 18
	v_or_b32_e32 v30, s24, v29
	v_lshl_add_u64 v[4:5], s[20:21], 0, v[8:9]
	v_readlane_b32 s24, v254, 19
	v_or_b32_e32 v4, v4, v0
	v_readlane_b32 s25, v254, 20
	v_readlane_b32 s26, v254, 21
	v_readlane_b32 s27, v254, 22
	v_lshl_add_u64 v[66:67], s[24:25], 0, v[4:5]
	v_lshl_add_u64 v[4:5], s[22:23], 0, v[8:9]
	v_or_b32_e32 v4, v4, v0
	v_lshl_add_u64 v[68:69], s[26:27], 0, v[4:5]
	v_lshl_add_u64 v[4:5], s[20:21], 0, v[14:15]
	v_or_b32_e32 v4, v4, v0
	v_lshl_add_u64 v[74:75], s[24:25], 0, v[4:5]
	v_lshl_add_u64 v[4:5], s[22:23], 0, v[14:15]
	v_or_b32_e32 v4, v4, v0
	v_lshl_add_u64 v[76:77], s[26:27], 0, v[4:5]
	v_lshl_add_u64 v[4:5], s[20:21], 0, v[20:21]
	v_or_b32_e32 v4, v4, v0
	v_lshl_add_u64 v[78:79], s[24:25], 0, v[4:5]
	v_lshl_add_u64 v[4:5], s[22:23], 0, v[20:21]
	v_or_b32_e32 v4, v4, v0
	v_lshl_add_u64 v[80:81], s[26:27], 0, v[4:5]
	v_lshl_add_u64 v[4:5], s[20:21], 0, v[2:3]
	v_lshl_add_u64 v[2:3], s[22:23], 0, v[2:3]
	v_lshlrev_b32_e32 v30, 7, v30
	v_lshlrev_b32_e32 v26, 4, v26
	v_lshlrev_b32_e32 v27, 4, v27
	v_lshlrev_b32_e32 v28, 7, v28
	v_or_b32_e32 v4, v4, v0
	v_or_b32_e32 v2, v2, v0
	v_mov_b32_e32 v50, 0
	v_or_b32_e32 v86, v30, v26
	v_or_b32_e32 v87, v30, v27
	v_or3_b32 v89, v28, v26, s91
	v_or3_b32 v88, v28, v27, s91
	v_lshl_add_u64 v[82:83], s[24:25], 0, v[4:5]
	v_lshl_add_u64 v[84:85], s[26:27], 0, v[2:3]
	s_mov_b64 s[22:23], 0
	s_mov_b32 s3, 0
	v_mov_b32_e32 v51, v50
	v_mov_b32_e32 v52, v50
	v_mov_b32_e32 v53, v50
	v_mov_b32_e32 v2, v50
	v_mov_b32_e32 v3, v50
	v_mov_b32_e32 v4, v50
	v_mov_b32_e32 v5, v50
	v_mov_b32_e32 v6, v50
	v_mov_b32_e32 v7, v50
	v_mov_b32_e32 v8, v50
	v_mov_b32_e32 v9, v50
	v_mov_b32_e32 v10, v50
	v_mov_b32_e32 v11, v50
	v_mov_b32_e32 v12, v50
	v_mov_b32_e32 v13, v50
	v_mov_b32_e32 v14, v50
	v_mov_b32_e32 v15, v50
	v_mov_b32_e32 v16, v50
	v_mov_b32_e32 v17, v50
	v_mov_b32_e32 v18, v50
	v_mov_b32_e32 v19, v50
	v_mov_b32_e32 v20, v50
	v_mov_b32_e32 v21, v50
	v_mov_b32_e32 v22, v50
	v_mov_b32_e32 v23, v50
	v_mov_b32_e32 v24, v50
	v_mov_b32_e32 v25, v50
	v_mov_b32_e32 v26, v50
	v_mov_b32_e32 v27, v50
	v_mov_b32_e32 v28, v50
	v_mov_b32_e32 v29, v50
	v_mov_b32_e32 v30, v50
	v_mov_b32_e32 v31, v50
	v_mov_b32_e32 v32, v50
	v_mov_b32_e32 v33, v50
	v_mov_b32_e32 v34, v50
	v_mov_b32_e32 v35, v50
	v_mov_b32_e32 v36, v50
	v_mov_b32_e32 v37, v50
	v_mov_b32_e32 v38, v50
	v_mov_b32_e32 v39, v50
	v_mov_b32_e32 v40, v50
	v_mov_b32_e32 v41, v50
	v_mov_b32_e32 v42, v50
	v_mov_b32_e32 v43, v50
	v_mov_b32_e32 v44, v50
	v_mov_b32_e32 v45, v50
	v_mov_b32_e32 v46, v50
	v_mov_b32_e32 v47, v50
	v_mov_b32_e32 v48, v50
	v_mov_b32_e32 v49, v50
	v_mov_b32_e32 v54, v50
	v_mov_b32_e32 v55, v50
	v_mov_b32_e32 v56, v50
	v_mov_b32_e32 v57, v50
	v_mov_b32_e32 v58, v50
	v_mov_b32_e32 v59, v50
	v_mov_b32_e32 v60, v50
	v_mov_b32_e32 v61, v50
	v_mov_b32_e32 v62, v50
	v_mov_b32_e32 v63, v50
	v_mov_b32_e32 v64, v50
	v_mov_b32_e32 v65, v50
	v_readlane_b32 s69, v251, 50
	v_readlane_b32 s70, v251, 51
	v_readlane_b32 s71, v251, 52
	v_readlane_b32 s74, v251, 55
	v_readlane_b32 s75, v251, 56
	v_readlane_b32 s76, v251, 57
	v_readlane_b32 s77, v251, 58
	v_readlane_b32 s78, v251, 59
	v_readlane_b32 s79, v251, 60
	v_readlane_b32 s80, v251, 61
	v_readlane_b32 s81, v251, 62
	v_readlane_b32 s82, v251, 63
	v_readlane_b32 s83, v252, 0

; DI int tid_() { int t = threadIdx.x; asm volatile("" : "+v"(t)); return t; }
; #define LASP __attribute__((address_space(3)))
; DI void gemm_dma(f32x4 (&acc)[4][4], const bf16_t* Ap, int lda, const bf16_t* Bp, int ldb, int K, char* lds) {
;   const int tid = tid_(), wave = __builtin_amdgcn_readfirstlane(tid >> 6), lane = tid & 63;
;   const int wm = wave >> 1, wn = wave & 1, l15 = lane & 15, quad = lane >> 4;
;   const int nk = K / 64;
;   const int lrow = lane >> 3, lpc = lane & 7;
;   const bf16_t* ga[4]; const bf16_t* gb[4];
; #pragma unroll
;   for (int i = 0; i < 4; ++i) {
;     const int row = (wave * 4 + i) * 8 + lrow; const int q = lpc ^ (row & 7);
;     ga[i] = Ap + (size_t)row * lda + q * 8; gb[i] = Bp + (size_t)row * ldb + q * 8;
;   }
;   auto issue = [&](int kt) {
;     char* sb = lds + (kt & 1) * 32768 + wave * 4096;
; #pragma unroll
;     for (int i = 0; i < 4; ++i) {
;       __builtin_amdgcn_global_load_lds((const unsigned*)(ga[i] + kt * 64), (LASP unsigned*)(sb + i * 1024), 16, 0, 0);
;       __builtin_amdgcn_global_load_lds((const unsigned*)(gb[i] + kt * 64), (LASP unsigned*)(sb + 16384 + i * 1024), 16, 0, 0);
;     }
;   };
;   const int sw = l15 & 7;
;   const unsigned lbase = (unsigned)(size_t)(LASP char*)lds;
;   const unsigned a0 = (unsigned)((wm * 64 + l15) * 128 + ((quad ^ sw) * 16)), a1 = (unsigned)((wm * 64 + l15) * 128 + (((4 + quad) ^ sw) * 16));
;   const unsigned b0 = 16384u + (unsigned)((wn * 64 + l15) * 128 + ((quad ^ sw) * 16)), b1 = 16384u + (unsigned)((wn * 64 + l15) * 128 + (((4 + quad) ^ sw) * 16));
;   asm volatile("s_waitcnt vmcnt(0)" ::: "memory");
;   __builtin_amdgcn_s_barrier();
;   asm volatile("" ::: "memory");
;   issue(0);
; DI void phase_out(const Params& p, int l, char* lds) {
;     ...
;   for (int r = 0;; ++r) {
;     const int g = xcd_tile(r, 128 * 8); if (g < 0) break;
;     int mt, nt; tile_decode(g, 128, 8, mt, nt);
;     f32x4 acc[4][4]; zero_acc(acc);
;     gemm_dma(acc, p.hn + (size_t)mt * 128 * DM, DM, p.wt_out + (size_t)nt * 128 * DM, DM, DM, lds);
.LBB0_784:
	s_lshr_b32 s24, s21, 3
	s_and_b32 s24, s24, 0xffffff8
	s_sub_i32 s25, 0x80, s24
	s_min_i32 s25, s25, 8
	s_abs_i32 s26, s25
	v_cvt_f32_u32_e32 v0, s26
	s_sub_i32 s30, 0, s26
	s_and_b32 s21, s21, 63
	s_ashr_i32 s27, s25, 31
	v_rcp_iflag_f32_e32 v0, v0
	v_readlane_b32 s68, v251, 49
	v_mov_b32_e32 v26, v212
	v_readlane_b32 s78, v251, 59
	v_mul_f32_e32 v0, 0x4f7ffffe, v0
	v_cvt_u32_f32_e32 v0, v0
	v_readlane_b32 s79, v251, 60
	v_bfe_u32 v27, v26, 4, 2
	v_readfirstlane_b32 s31, v0
	s_mul_i32 s30, s30, s31
	s_mul_hi_u32 s30, s31, s30
	s_add_i32 s31, s31, s30
	s_mul_hi_u32 s30, s21, s31
	s_mul_i32 s31, s30, s26
	s_sub_i32 s31, s21, s31
	s_add_i32 s38, s30, 1
	s_sub_i32 s39, s31, s26
	s_cmp_ge_u32 s31, s26
	s_cselect_b32 s30, s38, s30
	s_cselect_b32 s31, s39, s31
	s_add_i32 s38, s30, 1
	s_cmp_ge_u32 s31, s26
	s_cselect_b32 s26, s38, s30
	s_add_i32 s21, s24, s21
	s_xor_b32 s24, s26, s27
	s_sub_i32 s24, s24, s27
	s_mul_i32 s25, s24, s25
	s_sub_i32 s26, s21, s25
	s_ashr_i32 s27, s26, 31
	s_lshl_b64 s[40:41], s[26:27], 18
	s_add_u32 s38, s8, s40
	s_addc_u32 s39, s9, s41
	s_ashr_i32 s25, s24, 31
	s_lshl_b64 s[30:31], s[24:25], 18
	s_add_u32 s42, s78, s30
	v_readfirstlane_b32 s21, v26
	s_addc_u32 s43, s79, s31
	s_ashr_i32 s25, s21, 6
	v_bfe_u32 v0, v26, 3, 3
	s_waitcnt lgkmcnt(0)
	v_lshl_or_b32 v2, s25, 5, v0
	v_bitop3_b32 v0, v0, v26, 7 bitop3:0x78
	v_and_b32_e32 v28, 7, v26
	v_lshlrev_b32_e32 v0, 4, v0
	v_ashrrev_i32_e32 v3, 31, v2
	v_and_b32_e32 v29, 15, v26
	v_lshl_add_u64 v[4:5], s[38:39], 0, v[0:1]
	v_lshlrev_b64 v[8:9], 11, v[2:3]
	v_or_b32_e32 v14, 8, v2
	s_lshr_b32 s27, s21, 1
	v_bitop3_b32 v26, v27, v26, 7 bitop3:0x78
	v_bitop3_b32 v27, v27, v28, 4 bitop3:0x36
	v_and_or_b32 v28, s21, 64, v29
	s_lshl_b32 s21, s25, 12
	v_lshl_add_u64 v[6:7], s[42:43], 0, v[0:1]
	v_lshl_add_u64 v[10:11], v[4:5], 0, v[8:9]
	v_ashrrev_i32_e32 v15, 31, v14
	s_nop 0
	s_barrier
	s_add_i32 s25, s21, 0x4000
	s_mov_b32 m0, s21
	v_lshl_add_u64 v[12:13], v[6:7], 0, v[8:9]
	v_lshlrev_b64 v[14:15], 11, v[14:15]
	v_or_b32_e32 v20, 16, v2
	global_load_lds_dwordx4 v[10:11], off
	s_mov_b32 m0, s25
	v_lshl_add_u64 v[16:17], v[4:5], 0, v[14:15]
	v_ashrrev_i32_e32 v21, 31, v20
	global_load_lds_dwordx4 v[12:13], off
	s_or_b32 m0, s21, 0x400
	v_lshl_add_u64 v[18:19], v[6:7], 0, v[14:15]
	v_lshlrev_b64 v[20:21], 11, v[20:21]
	v_or_b32_e32 v2, 24, v2
	global_load_lds_dwordx4 v[16:17], off
	s_add_i32 m0, s21, 0x4400
	v_lshl_add_u64 v[22:23], v[4:5], 0, v[20:21]
	v_ashrrev_i32_e32 v3, 31, v2
	global_load_lds_dwordx4 v[18:19], off
	s_or_b32 m0, s21, 0x800
	v_lshl_add_u64 v[24:25], v[6:7], 0, v[20:21]
	v_lshlrev_b64 v[2:3], 11, v[2:3]
	global_load_lds_dwordx4 v[22:23], off
	s_add_i32 m0, s21, 0x4800
	v_lshl_add_u64 v[4:5], v[4:5], 0, v[2:3]
	global_load_lds_dwordx4 v[24:25], off
	s_or_b32 m0, s21, 0xc00
	v_lshl_add_u64 v[6:7], v[6:7], 0, v[2:3]
	global_load_lds_dwordx4 v[4:5], off
	s_add_i32 m0, s21, 0x4c00
	v_lshl_add_u64 v[4:5], s[40:41], 0, v[8:9]
	global_load_lds_dwordx4 v[6:7], off
	v_readlane_b32 s38, v254, 19
	v_or_b32_e32 v4, v4, v0
	v_readlane_b32 s39, v254, 20
	v_readlane_b32 s42, v254, 35
	v_readlane_b32 s43, v254, 36
	v_lshl_add_u64 v[66:67], s[38:39], 0, v[4:5]
	v_lshl_add_u64 v[4:5], s[30:31], 0, v[8:9]
	v_or_b32_e32 v4, v4, v0
	v_lshl_add_u64 v[68:69], s[42:43], 0, v[4:5]
	v_lshl_add_u64 v[4:5], s[40:41], 0, v[14:15]
	v_or_b32_e32 v4, v4, v0
	v_lshl_add_u64 v[70:71], s[38:39], 0, v[4:5]
	v_lshl_add_u64 v[4:5], s[30:31], 0, v[14:15]
	v_or_b32_e32 v4, v4, v0
	v_lshl_add_u64 v[72:73], s[42:43], 0, v[4:5]
	v_lshl_add_u64 v[4:5], s[40:41], 0, v[20:21]
	v_or_b32_e32 v4, v4, v0
	v_lshl_add_u64 v[74:75], s[38:39], 0, v[4:5]
	v_lshl_add_u64 v[4:5], s[30:31], 0, v[20:21]
	s_and_b32 s27, s27, 0x1ffffc0
	v_or_b32_e32 v4, v4, v0
	v_or_b32_e32 v30, s27, v29
	v_lshl_add_u64 v[76:77], s[42:43], 0, v[4:5]
	v_lshl_add_u64 v[4:5], s[40:41], 0, v[2:3]
	v_lshl_add_u64 v[2:3], s[30:31], 0, v[2:3]
	v_lshlrev_b32_e32 v30, 7, v30
	v_lshlrev_b32_e32 v26, 4, v26
	v_lshlrev_b32_e32 v27, 4, v27
	v_lshlrev_b32_e32 v28, 7, v28
	v_or_b32_e32 v4, v4, v0
	v_or_b32_e32 v2, v2, v0
	v_mov_b32_e32 v50, 0
	v_or_b32_e32 v84, v30, v26
	v_or_b32_e32 v85, v30, v27
	v_or3_b32 v87, v28, v26, s91
	v_or3_b32 v86, v28, v27, s91
	v_lshl_add_u64 v[78:79], s[38:39], 0, v[4:5]
	v_lshl_add_u64 v[80:81], s[42:43], 0, v[2:3]
	s_mov_b64 s[30:31], 0
	s_mov_b32 s25, 0
	v_mov_b32_e32 v51, v50
	v_mov_b32_e32 v52, v50
	v_mov_b32_e32 v53, v50
	v_mov_b32_e32 v2, v50
	v_mov_b32_e32 v3, v50
	v_mov_b32_e32 v4, v50
	v_mov_b32_e32 v5, v50
	v_mov_b32_e32 v6, v50
	v_mov_b32_e32 v7, v50
	v_mov_b32_e32 v8, v50
	v_mov_b32_e32 v9, v50
	v_mov_b32_e32 v10, v50
	v_mov_b32_e32 v11, v50
	v_mov_b32_e32 v12, v50
	v_mov_b32_e32 v13, v50
	v_mov_b32_e32 v14, v50
	v_mov_b32_e32 v15, v50
	v_mov_b32_e32 v16, v50
	v_mov_b32_e32 v17, v50
	v_mov_b32_e32 v18, v50
	v_mov_b32_e32 v19, v50
	v_mov_b32_e32 v20, v50
	v_mov_b32_e32 v21, v50
	v_mov_b32_e32 v22, v50
	v_mov_b32_e32 v23, v50
	v_mov_b32_e32 v24, v50
	v_mov_b32_e32 v25, v50
	v_mov_b32_e32 v26, v50
	v_mov_b32_e32 v27, v50
	v_mov_b32_e32 v28, v50
	v_mov_b32_e32 v29, v50
	v_mov_b32_e32 v30, v50
	v_mov_b32_e32 v31, v50
	v_mov_b32_e32 v32, v50
	v_mov_b32_e32 v33, v50
	v_mov_b32_e32 v34, v50
	v_mov_b32_e32 v35, v50
	v_mov_b32_e32 v36, v50
	v_mov_b32_e32 v37, v50
	v_mov_b32_e32 v38, v50
	v_mov_b32_e32 v39, v50
	v_mov_b32_e32 v40, v50
	v_mov_b32_e32 v41, v50
	v_mov_b32_e32 v42, v50
	v_mov_b32_e32 v43, v50
	v_mov_b32_e32 v44, v50
	v_mov_b32_e32 v45, v50
	v_mov_b32_e32 v46, v50
	v_mov_b32_e32 v47, v50
	v_mov_b32_e32 v48, v50
	v_mov_b32_e32 v49, v50
	v_mov_b32_e32 v54, v50
	v_mov_b32_e32 v55, v50
	v_mov_b32_e32 v56, v50
	v_mov_b32_e32 v57, v50
	v_mov_b32_e32 v58, v50
	v_mov_b32_e32 v59, v50
	v_mov_b32_e32 v60, v50
	v_mov_b32_e32 v61, v50
	v_mov_b32_e32 v62, v50
	v_mov_b32_e32 v63, v50
	v_mov_b32_e32 v64, v50
	v_mov_b32_e32 v65, v50
	v_readlane_b32 s69, v251, 50
	v_readlane_b32 s70, v251, 51
	v_readlane_b32 s71, v251, 52
	v_readlane_b32 s72, v251, 53
	v_readlane_b32 s73, v251, 54
	v_readlane_b32 s74, v251, 55
	v_readlane_b32 s75, v251, 56
	v_readlane_b32 s76, v251, 57
	v_readlane_b32 s77, v251, 58
	v_readlane_b32 s80, v251, 61
	v_readlane_b32 s81, v251, 62
	v_readlane_b32 s82, v251, 63
	v_readlane_b32 s83, v252, 0
	s_waitcnt vmcnt(0)

; DI int tid_() { int t = threadIdx.x; asm volatile("" : "+v"(t)); return t; }
; #define LASP __attribute__((address_space(3)))
; DI void gemm_dma(f32x4 (&acc)[4][4], const bf16_t* Ap, int lda, const bf16_t* Bp, int ldb, int K, char* lds) {
;   const int tid = tid_(), wave = __builtin_amdgcn_readfirstlane(tid >> 6), lane = tid & 63;
;   const int wm = wave >> 1, wn = wave & 1, l15 = lane & 15, quad = lane >> 4;
;   const int nk = K / 64;
;   const int lrow = lane >> 3, lpc = lane & 7;
;   const bf16_t* ga[4]; const bf16_t* gb[4];
; #pragma unroll
;   for (int i = 0; i < 4; ++i) {
;     const int row = (wave * 4 + i) * 8 + lrow; const int q = lpc ^ (row & 7);
;     ga[i] = Ap + (size_t)row * lda + q * 8; gb[i] = Bp + (size_t)row * ldb + q * 8;
;   }
;   auto issue = [&](int kt) {
;     char* sb = lds + (kt & 1) * 32768 + wave * 4096;
; #pragma unroll
;     for (int i = 0; i < 4; ++i) {
;       __builtin_amdgcn_global_load_lds((const unsigned*)(ga[i] + kt * 64), (LASP unsigned*)(sb + i * 1024), 16, 0, 0);
;       __builtin_amdgcn_global_load_lds((const unsigned*)(gb[i] + kt * 64), (LASP unsigned*)(sb + 16384 + i * 1024), 16, 0, 0);
;     }
;   };
;   const int sw = l15 & 7;
;   const unsigned lbase = (unsigned)(size_t)(LASP char*)lds;
;   const unsigned a0 = (unsigned)((wm * 64 + l15) * 128 + ((quad ^ sw) * 16)), a1 = (unsigned)((wm * 64 + l15) * 128 + (((4 + quad) ^ sw) * 16));
;   const unsigned b0 = 16384u + (unsigned)((wn * 64 + l15) * 128 + ((quad ^ sw) * 16)), b1 = 16384u + (unsigned)((wn * 64 + l15) * 128 + (((4 + quad) ^ sw) * 16));
;   asm volatile("s_waitcnt vmcnt(0)" ::: "memory");
;   __builtin_amdgcn_s_barrier();
;   asm volatile("" ::: "memory");
;   issue(0);
; DI void phase_ple(const Params& p, int l, char* lds) {
;     ...
;   for (int r = 0;; ++r) {
;     const int g = xcd_tile(r, 128 * 8); if (g < 0) break;
;     int mt, nt; tile_decode(g, 128, 8, mt, nt);
;     f32x4 a1[4][4]; zero_acc(a1);
;     gemm_dma(a1, p.o_r + (size_t)mt * 128 * DM, DM, p.wt_gate + (size_t)nt * 128 * DM, DM, DM, lds);
.LBB0_902:
	s_lshr_b32 s1, s0, 3
	s_and_b32 s1, s1, 0xffffff8
	s_sub_i32 s21, 0x80, s1
	s_min_i32 s21, s21, 8
	s_abs_i32 s26, s21
	v_cvt_f32_u32_e32 v0, s26
	s_sub_i32 s30, 0, s26
	s_and_b32 s0, s0, 63
	s_ashr_i32 s27, s21, 31
	v_rcp_iflag_f32_e32 v0, v0
	v_readlane_b32 s68, v251, 49
	v_mov_b32_e32 v26, v212
	v_readlane_b32 s82, v251, 63
	v_mul_f32_e32 v0, 0x4f7ffffe, v0
	v_cvt_u32_f32_e32 v0, v0
	v_readlane_b32 s83, v252, 0
	v_bfe_u32 v27, v26, 4, 2
	v_readfirstlane_b32 s31, v0
	s_mul_i32 s30, s30, s31
	s_mul_hi_u32 s30, s31, s30
	s_add_i32 s31, s31, s30
	s_mul_hi_u32 s30, s0, s31
	s_mul_i32 s31, s30, s26
	s_sub_i32 s31, s0, s31
	s_add_i32 s40, s30, 1
	s_sub_i32 s41, s31, s26
	s_cmp_ge_u32 s31, s26
	s_cselect_b32 s30, s40, s30
	s_cselect_b32 s31, s41, s31
	s_add_i32 s40, s30, 1
	s_cmp_ge_u32 s31, s26
	s_cselect_b32 s26, s40, s30
	s_add_i32 s1, s1, s0
	s_xor_b32 s0, s26, s27
	s_sub_i32 s0, s0, s27
	s_mul_i32 s21, s0, s21
	s_sub_i32 s26, s1, s21
	s_ashr_i32 s27, s26, 31
	s_lshl_b64 s[40:41], s[26:27], 18
	s_add_u32 s42, s52, s40
	s_addc_u32 s43, s53, s41
	s_ashr_i32 s1, s0, 31
	s_lshl_b64 s[30:31], s[0:1], 18
	s_add_u32 s44, s82, s30
	v_readfirstlane_b32 s21, v26
	s_addc_u32 s45, s83, s31
	s_ashr_i32 s27, s21, 6
	v_bfe_u32 v0, v26, 3, 3
	s_waitcnt lgkmcnt(0)
	v_lshl_or_b32 v2, s27, 5, v0
	v_bitop3_b32 v0, v0, v26, 7 bitop3:0x78
	v_and_b32_e32 v28, 7, v26
	v_lshlrev_b32_e32 v0, 4, v0
	v_ashrrev_i32_e32 v3, 31, v2
	v_and_b32_e32 v29, 15, v26
	v_lshl_add_u64 v[4:5], s[42:43], 0, v[0:1]
	v_lshlrev_b64 v[8:9], 11, v[2:3]
	v_or_b32_e32 v14, 8, v2
	s_lshr_b32 s42, s21, 1
	v_bitop3_b32 v26, v27, v26, 7 bitop3:0x78
	v_bitop3_b32 v27, v27, v28, 4 bitop3:0x36
	v_and_or_b32 v28, s21, 64, v29
	s_lshl_b32 s21, s27, 12
	v_lshl_add_u64 v[6:7], s[44:45], 0, v[0:1]
	v_lshl_add_u64 v[10:11], v[4:5], 0, v[8:9]
	v_ashrrev_i32_e32 v15, 31, v14
	s_nop 0
	s_barrier
	s_add_i32 s27, s21, 0x4000
	s_mov_b32 m0, s21
	v_lshl_add_u64 v[12:13], v[6:7], 0, v[8:9]
	v_lshlrev_b64 v[14:15], 11, v[14:15]
	v_or_b32_e32 v20, 16, v2
	global_load_lds_dwordx4 v[10:11], off
	s_mov_b32 m0, s27
	v_lshl_add_u64 v[16:17], v[4:5], 0, v[14:15]
	v_ashrrev_i32_e32 v21, 31, v20
	global_load_lds_dwordx4 v[12:13], off
	s_or_b32 m0, s21, 0x400
	v_lshl_add_u64 v[18:19], v[6:7], 0, v[14:15]
	v_lshlrev_b64 v[20:21], 11, v[20:21]
	v_or_b32_e32 v2, 24, v2
	global_load_lds_dwordx4 v[16:17], off
	s_add_i32 m0, s21, 0x4400
	v_lshl_add_u64 v[22:23], v[4:5], 0, v[20:21]
	v_ashrrev_i32_e32 v3, 31, v2
	global_load_lds_dwordx4 v[18:19], off
	s_or_b32 m0, s21, 0x800
	v_lshl_add_u64 v[24:25], v[6:7], 0, v[20:21]
	v_lshlrev_b64 v[2:3], 11, v[2:3]
	global_load_lds_dwordx4 v[22:23], off
	s_add_i32 m0, s21, 0x4800
	v_lshl_add_u64 v[4:5], v[4:5], 0, v[2:3]
	global_load_lds_dwordx4 v[24:25], off
	s_or_b32 m0, s21, 0xc00
	v_lshl_add_u64 v[6:7], v[6:7], 0, v[2:3]
	global_load_lds_dwordx4 v[4:5], off
	s_add_i32 m0, s21, 0x4c00
	s_and_b32 s42, s42, 0x1ffffc0
	global_load_lds_dwordx4 v[6:7], off
	v_or_b32_e32 v30, s42, v29
	v_lshl_add_u64 v[4:5], s[40:41], 0, v[8:9]
	v_readlane_b32 s42, v254, 37
	v_or_b32_e32 v4, v4, v0
	v_readlane_b32 s43, v254, 38
	v_readlane_b32 s44, v254, 39
	v_readlane_b32 s45, v254, 40
	v_lshl_add_u64 v[66:67], s[42:43], 0, v[4:5]
	v_lshl_add_u64 v[4:5], s[30:31], 0, v[8:9]
	v_or_b32_e32 v4, v4, v0
	v_lshl_add_u64 v[68:69], s[44:45], 0, v[4:5]
	v_lshl_add_u64 v[4:5], s[40:41], 0, v[14:15]
	v_or_b32_e32 v4, v4, v0
	v_lshl_add_u64 v[70:71], s[42:43], 0, v[4:5]
	v_lshl_add_u64 v[4:5], s[30:31], 0, v[14:15]
	v_or_b32_e32 v4, v4, v0
	v_lshl_add_u64 v[72:73], s[44:45], 0, v[4:5]
	v_lshl_add_u64 v[4:5], s[40:41], 0, v[20:21]
	v_or_b32_e32 v4, v4, v0
	v_lshl_add_u64 v[74:75], s[42:43], 0, v[4:5]
	v_lshl_add_u64 v[4:5], s[30:31], 0, v[20:21]
	v_or_b32_e32 v4, v4, v0
	v_lshl_add_u64 v[76:77], s[44:45], 0, v[4:5]
	v_lshl_add_u64 v[4:5], s[40:41], 0, v[2:3]
	v_lshl_add_u64 v[2:3], s[30:31], 0, v[2:3]
	v_lshlrev_b32_e32 v30, 7, v30
	v_lshlrev_b32_e32 v26, 4, v26
	v_lshlrev_b32_e32 v27, 4, v27
	v_lshlrev_b32_e32 v28, 7, v28
	v_or_b32_e32 v4, v4, v0
	v_or_b32_e32 v2, v2, v0
	v_mov_b32_e32 v50, 0
	v_or_b32_e32 v82, v30, v26
	v_or_b32_e32 v83, v30, v27
	v_or3_b32 v85, v28, v26, s91
	v_or3_b32 v84, v28, v27, s91
	v_lshl_add_u64 v[78:79], s[42:43], 0, v[4:5]
	v_lshl_add_u64 v[80:81], s[44:45], 0, v[2:3]
	s_mov_b64 s[30:31], 0
	s_mov_b32 s27, 0
	v_mov_b32_e32 v51, v50
	v_mov_b32_e32 v52, v50
	v_mov_b32_e32 v53, v50
	v_mov_b32_e32 v2, v50
	v_mov_b32_e32 v3, v50
	v_mov_b32_e32 v4, v50
	v_mov_b32_e32 v5, v50
	v_mov_b32_e32 v6, v50
	v_mov_b32_e32 v7, v50
	v_mov_b32_e32 v8, v50
	v_mov_b32_e32 v9, v50
	v_mov_b32_e32 v10, v50
	v_mov_b32_e32 v11, v50
	v_mov_b32_e32 v12, v50
	v_mov_b32_e32 v13, v50
	v_mov_b32_e32 v14, v50
	v_mov_b32_e32 v15, v50
	v_mov_b32_e32 v16, v50
	v_mov_b32_e32 v17, v50
	v_mov_b32_e32 v18, v50
	v_mov_b32_e32 v19, v50
	v_mov_b32_e32 v20, v50
	v_mov_b32_e32 v21, v50
	v_mov_b32_e32 v22, v50
	v_mov_b32_e32 v23, v50
	v_mov_b32_e32 v24, v50
	v_mov_b32_e32 v25, v50
	v_mov_b32_e32 v26, v50
	v_mov_b32_e32 v27, v50
	v_mov_b32_e32 v28, v50
	v_mov_b32_e32 v29, v50
	v_mov_b32_e32 v30, v50
	v_mov_b32_e32 v31, v50
	v_mov_b32_e32 v32, v50
	v_mov_b32_e32 v33, v50
	v_mov_b32_e32 v34, v50
	v_mov_b32_e32 v35, v50
	v_mov_b32_e32 v36, v50
	v_mov_b32_e32 v37, v50
	v_mov_b32_e32 v38, v50
	v_mov_b32_e32 v39, v50
	v_mov_b32_e32 v40, v50
	v_mov_b32_e32 v41, v50
	v_mov_b32_e32 v42, v50
	v_mov_b32_e32 v43, v50
	v_mov_b32_e32 v44, v50
	v_mov_b32_e32 v45, v50
	v_mov_b32_e32 v46, v50
	v_mov_b32_e32 v47, v50
	v_mov_b32_e32 v48, v50
	v_mov_b32_e32 v49, v50
	v_mov_b32_e32 v54, v50
	v_mov_b32_e32 v55, v50
	v_mov_b32_e32 v56, v50
	v_mov_b32_e32 v57, v50
	v_mov_b32_e32 v58, v50
	v_mov_b32_e32 v59, v50
	v_mov_b32_e32 v60, v50
	v_mov_b32_e32 v61, v50
	v_mov_b32_e32 v62, v50
	v_mov_b32_e32 v63, v50
	v_mov_b32_e32 v64, v50
	v_mov_b32_e32 v65, v50
	v_readlane_b32 s69, v251, 50
	v_readlane_b32 s70, v251, 51
	v_readlane_b32 s71, v251, 52
	v_readlane_b32 s72, v251, 53
	v_readlane_b32 s73, v251, 54
	v_readlane_b32 s74, v251, 55
	v_readlane_b32 s75, v251, 56
	v_readlane_b32 s76, v251, 57
	v_readlane_b32 s77, v251, 58
	v_readlane_b32 s78, v251, 59
	v_readlane_b32 s79, v251, 60
	v_readlane_b32 s80, v251, 61
	v_readlane_b32 s81, v251, 62
	s_waitcnt vmcnt(0)
